# FFN epilogue: conv weights for n=0 issued before the LDS exchange barrier and for n=1 under the n=0 SiLU (hides two L2 round trips per tile)
# speedup vs baseline: 1.0282x; 1.0001x over previous
;     __device__ __forceinline__ void operator()(const f32x4 (&acc)[2][2][4][2], const Unit& u, int wr, int wc, int fr, int fq) const {
;     ...
;         asm volatile("s_waitcnt lgkmcnt(0)" ::: "memory"); __builtin_amdgcn_s_barrier(); asm volatile("" ::: "memory");
;         u32x2 keep[2][4];
; #pragma unroll
;         for (int n = 0; n < 2; ++n) {
;             const int ch0 = u.pn * HALF + wc * 32 + 8 * fq + 4 * n;
;             f32x4 w0[2], w1[2], w2[2], bb[2];
; #pragma unroll
;             for (int bj = 0; bj < 2; ++bj) { w0[bj] = *(const f32x4*)(cw + bj * dff + ch0); w1[bj] = *(const f32x4*)(cw + upw + bj * dff + ch0); w2[bj] = *(const f32x4*)(cw + 2 * upw + bj * dff + ch0); bb[bj] = *(const f32x4*)(cb + bj * dff + ch0); }
.Lffn_a2:
	s_or_b64 exec, exec, s[72:73]
	s_lshl_b32 s1, s0, 9
	s_lshl_b32 s22, s81, 7
	s_add_i32 s1, s1, s22
	v_lshl_add_u32 v112, v192, 2, s1
	v_add_u32_e32 v113, 0x5800, v112
	global_load_dwordx4 v[126:129], v112, s[26:27]
	global_load_dwordx4 v[130:133], v113, s[26:27]
	global_load_dwordx4 v[134:137], v112, s[58:59]
	global_load_dwordx4 v[138:141], v113, s[58:59]
	global_load_dwordx4 v[142:145], v112, s[60:61]
	global_load_dwordx4 v[146:149], v113, s[60:61]
	global_load_dwordx4 v[150:153], v112, s[44:45]
	global_load_dwordx4 v[154:157], v113, s[44:45]
	s_mul_i32 s1, s70, 0x2c0000
	s_lshl_b32 s22, s0, 8
	s_add_i32 s1, s1, s22
	s_lshl_b32 s22, s81, 6
	s_add_i32 s1, s1, s22
	s_add_u32 s30, s12, s1
	s_addc_u32 s31, s13, 0
	s_and_b64 vcc, exec, s[36:37]
	s_cbranch_vccz .Lffn_b0
	s_add_u32 s30, s30, 0xb0000
	s_addc_u32 s31, s31, 0
.Lffn_b0:
	v_mul_u32_u24_e32 v188, 0xb000, v190
	v_add_u32_e32 v188, v212, v188
	s_mov_b32 s71, 0xbfb8aa3b
	s_waitcnt lgkmcnt(0)
	s_barrier
	v_mov_b32_e32 v166, 0
	v_mov_b32_e32 v174, 0
	v_mov_b32_e32 v167, 0
	v_mov_b32_e32 v175, 0
	v_mov_b32_e32 v168, 0
	v_mov_b32_e32 v176, 0
	v_mov_b32_e32 v169, 0
	v_mov_b32_e32 v177, 0
	v_mov_b32_e32 v170, 0
	v_mov_b32_e32 v118, 0
	v_mov_b32_e32 v171, 0
	v_mov_b32_e32 v119, 0
	v_mov_b32_e32 v172, 0
	v_mov_b32_e32 v120, 0
	v_mov_b32_e32 v173, 0
	v_mov_b32_e32 v121, 0
	s_and_b64 vcc, exec, s[36:37]
	s_cbranch_vccz .Lffn_h00
	ds_read_b128 v[166:169], v214
	ds_read_b128 v[174:177], v214 offset:256
	ds_read_b128 v[170:173], v214 offset:128
	ds_read_b128 v[118:121], v214 offset:384

; #define PG8_LAS __attribute__((address_space(3)))
;     __device__ __forceinline__ void operator()(const f32x4 (&acc)[2][2][4][2], const Unit& u, int wr, int wc, int fr, int fq) const {
;     ...
;                 if (wr == 1 || ai == 1) { const int src = (wr == 1) ? (ai * 2 + 0) : (0 * 2 + 1);
; #pragma unroll
;                     for (int bj = 0; bj < 2; ++bj) { h14[bj] = *(const PG8_LAS f32x4*)(xch + (src * 4 + wc) * 128 + 0 * 64 + (bj * 2 + n) * 16 + fq * 4); h15[bj] = *(const PG8_LAS f32x4*)(xch + (src * 4 + wc) * 128 + 1 * 64 + (bj * 2 + n) * 16 + fq * 4); }
;                 } else {
; #pragma unroll
;                     for (int bj = 0; bj < 2; ++bj) { h14[bj] = (f32x4){0.f, 0.f, 0.f, 0.f}; h15[bj] = (f32x4){0.f, 0.f, 0.f, 0.f}; } }
; #pragma unroll
;                 for (int m = 0; m < 4; ++m) {
;                     float val[2][4];
; #pragma unroll
;                     for (int bj = 0; bj < 2; ++bj)
; #pragma unroll
;                         for (int jj = 0; jj < 4; ++jj) {
;                             const float cur = acc[ai][bj][m][n][jj];
;                             float o1, o2;
;                             if (m > 0) { const float pv = acc[ai][bj][m > 0 ? m - 1 : 0][n][jj]; o1 = dppf<0x121>(0.f, pv); o2 = dppf<0x122>(0.f, pv); }
;                             else { o1 = h15[bj][jj]; o2 = (fr == 0) ? h14[bj][jj] : h15[bj][jj]; }
;                             const float p1 = dppf<0x111>(o1, cur), p2 = dppf<0x112>(o2, cur);
;                             val[bj][jj] = w2[bj][jj] * cur + w1[bj][jj] * p1 + w0[bj][jj] * p2 + bb[bj][jj];
;                         }
.Lffn_hs:
	v_add_u32_e32 v206, s1, v214
	ds_read_b128 v[166:169], v206
	ds_read_b128 v[174:177], v206 offset:256
	ds_read_b128 v[170:173], v206 offset:128
	ds_read_b128 v[118:121], v206 offset:384
	s_waitcnt lgkmcnt(0)
	v_mov_b32_dpp v174, v72 row_shr:1 row_mask:0xf bank_mask:0xf
	v_mov_b32_dpp v175, v73 row_shr:1 row_mask:0xf bank_mask:0xf
	v_mov_b32_dpp v176, v74 row_shr:1 row_mask:0xf bank_mask:0xf
	v_mov_b32_dpp v177, v75 row_shr:1 row_mask:0xf bank_mask:0xf
	v_mov_b32_dpp v166, v76 row_shr:1 row_mask:0xf bank_mask:0xf
	v_mov_b32_dpp v167, v77 row_shr:1 row_mask:0xf bank_mask:0xf
	v_mov_b32_dpp v168, v78 row_shr:1 row_mask:0xf bank_mask:0xf
	v_mov_b32_dpp v169, v79 row_shr:1 row_mask:0xf bank_mask:0xf
	v_pk_fma_f32 v[72:73], v[142:143], v[72:73], v[150:151]
	v_pk_fma_f32 v[74:75], v[144:145], v[74:75], v[152:153]
	v_pk_fma_f32 v[72:73], v[134:135], v[76:77], v[72:73]
	v_pk_fma_f32 v[74:75], v[136:137], v[78:79], v[74:75]
	v_pk_fma_f32 v[72:73], v[126:127], v[84:85], v[72:73]
	v_pk_fma_f32 v[74:75], v[128:129], v[86:87], v[74:75]
	v_pk_fma_f32 v[76:77], v[142:143], v[76:77], v[150:151]
	v_pk_fma_f32 v[78:79], v[144:145], v[78:79], v[152:153]
	v_pk_fma_f32 v[76:77], v[134:135], v[84:85], v[76:77]
	v_pk_fma_f32 v[78:79], v[136:137], v[86:87], v[78:79]
	v_pk_fma_f32 v[76:77], v[126:127], v[92:93], v[76:77]
	v_pk_fma_f32 v[78:79], v[128:129], v[94:95], v[78:79]
	v_pk_fma_f32 v[84:85], v[142:143], v[84:85], v[150:151]
	v_pk_fma_f32 v[86:87], v[144:145], v[86:87], v[152:153]
	v_pk_fma_f32 v[84:85], v[134:135], v[92:93], v[84:85]
	v_pk_fma_f32 v[86:87], v[136:137], v[94:95], v[86:87]
	v_pk_fma_f32 v[84:85], v[126:127], v[174:175], v[84:85]
	v_pk_fma_f32 v[86:87], v[128:129], v[176:177], v[86:87]
	v_pk_fma_f32 v[92:93], v[142:143], v[92:93], v[150:151]
	v_pk_fma_f32 v[94:95], v[144:145], v[94:95], v[152:153]
	v_pk_fma_f32 v[92:93], v[134:135], v[174:175], v[92:93]
	v_pk_fma_f32 v[94:95], v[136:137], v[176:177], v[94:95]
	v_pk_fma_f32 v[92:93], v[126:127], v[166:167], v[92:93]
	v_pk_fma_f32 v[94:95], v[128:129], v[168:169], v[94:95]
	v_mov_b32_dpp v118, v64 row_shr:1 row_mask:0xf bank_mask:0xf
	v_mov_b32_dpp v119, v65 row_shr:1 row_mask:0xf bank_mask:0xf
	v_mov_b32_dpp v120, v66 row_shr:1 row_mask:0xf bank_mask:0xf
	v_mov_b32_dpp v121, v67 row_shr:1 row_mask:0xf bank_mask:0xf
	v_mov_b32_dpp v170, v68 row_shr:1 row_mask:0xf bank_mask:0xf
	v_mov_b32_dpp v171, v69 row_shr:1 row_mask:0xf bank_mask:0xf
	v_mov_b32_dpp v172, v70 row_shr:1 row_mask:0xf bank_mask:0xf
	v_mov_b32_dpp v173, v71 row_shr:1 row_mask:0xf bank_mask:0xf
	v_pk_fma_f32 v[64:65], v[146:147], v[64:65], v[154:155]
	v_pk_fma_f32 v[66:67], v[148:149], v[66:67], v[156:157]
	v_pk_fma_f32 v[64:65], v[138:139], v[68:69], v[64:65]
	v_pk_fma_f32 v[66:67], v[140:141], v[70:71], v[66:67]
	v_pk_fma_f32 v[64:65], v[130:131], v[80:81], v[64:65]
	v_pk_fma_f32 v[66:67], v[132:133], v[82:83], v[66:67]
	v_pk_fma_f32 v[68:69], v[146:147], v[68:69], v[154:155]
	v_pk_fma_f32 v[70:71], v[148:149], v[70:71], v[156:157]
	v_pk_fma_f32 v[68:69], v[138:139], v[80:81], v[68:69]
	v_pk_fma_f32 v[70:71], v[140:141], v[82:83], v[70:71]
	v_pk_fma_f32 v[68:69], v[130:131], v[88:89], v[68:69]
	v_pk_fma_f32 v[70:71], v[132:133], v[90:91], v[70:71]
	v_pk_fma_f32 v[80:81], v[146:147], v[80:81], v[154:155]
	v_pk_fma_f32 v[82:83], v[148:149], v[82:83], v[156:157]
	v_pk_fma_f32 v[80:81], v[138:139], v[88:89], v[80:81]
	v_pk_fma_f32 v[82:83], v[140:141], v[90:91], v[82:83]
	v_pk_fma_f32 v[80:81], v[130:131], v[118:119], v[80:81]
	v_pk_fma_f32 v[82:83], v[132:133], v[120:121], v[82:83]
	v_pk_fma_f32 v[88:89], v[146:147], v[88:89], v[154:155]
	v_pk_fma_f32 v[90:91], v[148:149], v[90:91], v[156:157]
	v_pk_fma_f32 v[88:89], v[138:139], v[118:119], v[88:89]
	v_pk_fma_f32 v[90:91], v[140:141], v[120:121], v[90:91]
	v_pk_fma_f32 v[88:89], v[130:131], v[170:171], v[88:89]
	v_pk_fma_f32 v[90:91], v[132:133], v[172:173], v[90:91]
; #define PG8_LAS __attribute__((address_space(3)))
;     __device__ __forceinline__ void operator()(const f32x4 (&acc)[2][2][4][2], const Unit& u, int wr, int wc, int fr, int fq) const {
;     ...
;         for (int n = 0; n < 2; ++n) {
;             const int ch0 = u.pn * HALF + wc * 32 + 8 * fq + 4 * n;
;             f32x4 w0[2], w1[2], w2[2], bb[2];
; #pragma unroll
;             for (int bj = 0; bj < 2; ++bj) { w0[bj] = *(const f32x4*)(cw + bj * dff + ch0); w1[bj] = *(const f32x4*)(cw + upw + bj * dff + ch0); w2[bj] = *(const f32x4*)(cw + 2 * upw + bj * dff + ch0); bb[bj] = *(const f32x4*)(cb + bj * dff + ch0); }
; #pragma unroll
;             for (int ai = 0; ai < 2; ++ai) {
;                 f32x4 h15[2], h14[2];
;                 if (wr == 1 || ai == 1) { const int src = (wr == 1) ? (ai * 2 + 0) : (0 * 2 + 1);
; #pragma unroll
;                     for (int bj = 0; bj < 2; ++bj) { h14[bj] = *(const PG8_LAS f32x4*)(xch + (src * 4 + wc) * 128 + 0 * 64 + (bj * 2 + n) * 16 + fq * 4); h15[bj] = *(const PG8_LAS f32x4*)(xch + (src * 4 + wc) * 128 + 1 * 64 + (bj * 2 + n) * 16 + fq * 4); }
;                 } else {
; #pragma unroll
;                     for (int bj = 0; bj < 2; ++bj) { h14[bj] = (f32x4){0.f, 0.f, 0.f, 0.f}; h15[bj] = (f32x4){0.f, 0.f, 0.f, 0.f}; } }
; #pragma unroll
;                 for (int m = 0; m < 4; ++m) {
;                     float val[2][4];
; #pragma unroll
;                     for (int bj = 0; bj < 2; ++bj)
; #pragma unroll
;                         for (int jj = 0; jj < 4; ++jj) {
;                             const float cur = acc[ai][bj][m][n][jj];
;                             float o1, o2;
;                             if (m > 0) { const float pv = acc[ai][bj][m > 0 ? m - 1 : 0][n][jj]; o1 = dppf<0x121>(0.f, pv); o2 = dppf<0x122>(0.f, pv); }
;                             else { o1 = h15[bj][jj]; o2 = (fr == 0) ? h14[bj][jj] : h15[bj][jj]; }
;                             const float p1 = dppf<0x111>(o1, cur), p2 = dppf<0x112>(o2, cur);
;                             val[bj][jj] = w2[bj][jj] * cur + w1[bj][jj] * p1 + w0[bj][jj] * p2 + bb[bj][jj];
;                         }
;                     float y[4];
; #pragma unroll
;                     for (int jj = 0; jj < 4; ++jj) { const float g = val[1][jj]; y[jj] = val[0][jj] * g * __builtin_amdgcn_rcpf(1.0f + __builtin_amdgcn_exp2f(-1.4426950408889634f * g)); }
	global_load_dwordx4 v[126:129], v112, s[26:27] offset:16
	global_load_dwordx4 v[130:133], v113, s[26:27] offset:16
	global_load_dwordx4 v[134:137], v112, s[58:59] offset:16
	global_load_dwordx4 v[138:141], v113, s[58:59] offset:16
	global_load_dwordx4 v[142:145], v112, s[60:61] offset:16
	global_load_dwordx4 v[146:149], v113, s[60:61] offset:16
	global_load_dwordx4 v[150:153], v112, s[44:45] offset:16
	global_load_dwordx4 v[154:157], v113, s[44:45] offset:16
	v_mul_f32_e32 v208, s71, v88
	v_mul_f32_e32 v209, s71, v89
	v_mul_f32_e32 v210, s71, v90
	v_mul_f32_e32 v211, s71, v91
	v_exp_f32_e32 v208, v208
	v_exp_f32_e32 v209, v209
	v_exp_f32_e32 v210, v210
	v_exp_f32_e32 v211, v211
	v_pk_mul_f32 v[92:93], v[92:93], v[88:89]
	v_pk_mul_f32 v[94:95], v[94:95], v[90:91]
	v_add_f32_e32 v208, 1.0, v208
	v_add_f32_e32 v209, 1.0, v209
	v_add_f32_e32 v210, 1.0, v210
	v_add_f32_e32 v211, 1.0, v211
	v_rcp_f32_e32 v208, v208
	v_rcp_f32_e32 v209, v209
	v_rcp_f32_e32 v210, v210
	v_rcp_f32_e32 v211, v211
	s_nop 0
	v_pk_mul_f32 v[92:93], v[92:93], v[208:209]
	v_pk_mul_f32 v[94:95], v[94:95], v[210:211]
	v_cvt_pk_bf16_f32 v88, v92, v93
	v_cvt_pk_bf16_f32 v89, v94, v95
	v_mul_f32_e32 v208, s71, v80
	v_mul_f32_e32 v209, s71, v81
	v_mul_f32_e32 v210, s71, v82
	v_mul_f32_e32 v211, s71, v83
	v_exp_f32_e32 v208, v208
	v_exp_f32_e32 v209, v209
	v_exp_f32_e32 v210, v210
	v_exp_f32_e32 v211, v211
	v_pk_mul_f32 v[84:85], v[84:85], v[80:81]
	v_pk_mul_f32 v[86:87], v[86:87], v[82:83]
	v_add_f32_e32 v208, 1.0, v208
	v_add_f32_e32 v209, 1.0, v209
	v_add_f32_e32 v210, 1.0, v210
	v_add_f32_e32 v211, 1.0, v211
	v_rcp_f32_e32 v208, v208
	v_rcp_f32_e32 v209, v209
	v_rcp_f32_e32 v210, v210
	v_rcp_f32_e32 v211, v211
	s_nop 0
	v_pk_mul_f32 v[84:85], v[84:85], v[208:209]
	v_pk_mul_f32 v[86:87], v[86:87], v[210:211]
	v_cvt_pk_bf16_f32 v80, v84, v85
	v_cvt_pk_bf16_f32 v81, v86, v87
	v_mul_f32_e32 v208, s71, v68
	v_mul_f32_e32 v209, s71, v69
	v_mul_f32_e32 v210, s71, v70
	v_mul_f32_e32 v211, s71, v71
	v_exp_f32_e32 v208, v208
	v_exp_f32_e32 v209, v209
	v_exp_f32_e32 v210, v210
	v_exp_f32_e32 v211, v211
	v_pk_mul_f32 v[76:77], v[76:77], v[68:69]
	v_pk_mul_f32 v[78:79], v[78:79], v[70:71]
	v_add_f32_e32 v208, 1.0, v208
	v_add_f32_e32 v209, 1.0, v209
	v_add_f32_e32 v210, 1.0, v210
	v_add_f32_e32 v211, 1.0, v211
	v_rcp_f32_e32 v208, v208
	v_rcp_f32_e32 v209, v209
	v_rcp_f32_e32 v210, v210
	v_rcp_f32_e32 v211, v211
	s_nop 0
	v_pk_mul_f32 v[76:77], v[76:77], v[208:209]
	v_pk_mul_f32 v[78:79], v[78:79], v[210:211]
	v_cvt_pk_bf16_f32 v68, v76, v77
	v_cvt_pk_bf16_f32 v69, v78, v79
	v_mul_f32_e32 v208, s71, v64
	v_mul_f32_e32 v209, s71, v65
	v_mul_f32_e32 v210, s71, v66
	v_mul_f32_e32 v211, s71, v67
	v_exp_f32_e32 v208, v208
	v_exp_f32_e32 v209, v209
	v_exp_f32_e32 v210, v210
	v_exp_f32_e32 v211, v211
	v_pk_mul_f32 v[72:73], v[72:73], v[64:65]
	v_pk_mul_f32 v[74:75], v[74:75], v[66:67]
	v_add_f32_e32 v208, 1.0, v208
	v_add_f32_e32 v209, 1.0, v209
	v_add_f32_e32 v210, 1.0, v210
	v_add_f32_e32 v211, 1.0, v211
	v_rcp_f32_e32 v208, v208
	v_rcp_f32_e32 v209, v209
	v_rcp_f32_e32 v210, v210
	v_rcp_f32_e32 v211, v211
	s_nop 0
	v_pk_mul_f32 v[72:73], v[72:73], v[208:209]
	v_pk_mul_f32 v[74:75], v[74:75], v[210:211]
	v_cvt_pk_bf16_f32 v64, v72, v73
	v_cvt_pk_bf16_f32 v65, v74, v75
	v_mov_b32_e32 v166, 0
	v_mov_b32_e32 v174, 0
	v_mov_b32_e32 v167, 0
	v_mov_b32_e32 v175, 0
	v_mov_b32_e32 v168, 0
	v_mov_b32_e32 v176, 0
	v_mov_b32_e32 v169, 0
	v_mov_b32_e32 v177, 0
	v_mov_b32_e32 v170, 0
	v_mov_b32_e32 v118, 0
	v_mov_b32_e32 v171, 0
	v_mov_b32_e32 v119, 0
	v_mov_b32_e32 v172, 0
	v_mov_b32_e32 v120, 0
	v_mov_b32_e32 v173, 0
	v_mov_b32_e32 v121, 0
	s_and_b64 vcc, exec, s[36:37]
	s_cbranch_vccz .Lffn_h10
	ds_read_b128 v[166:169], v214 offset:64
	ds_read_b128 v[174:177], v214 offset:320
	ds_read_b128 v[170:173], v214 offset:192
	ds_read_b128 v[118:121], v214 offset:448
